# attention loop: packed f32 accumulator-rescale multiplies beside the MFMAs split into scalar pairs
# speedup vs baseline: 1.0017x; 1.0017x over previous
.LBB0_29:
	s_add_i32 s29, s41, 1
	s_movk_i32 s30, 0xe000
	v_add_co_u32_e32 v60, vcc, s30, v96
	s_bitcmp1_b32 s41, 0
	s_mov_b64 s[30:31], 0x4000
	global_load_dwordx4 v[40:43], v[96:97], off
	global_load_dwordx4 v[32:35], v[98:99], off
	global_load_dwordx4 v[36:39], v[100:101], off
	v_addc_co_u32_e32 v61, vcc, -1, v97, vcc
	v_lshl_add_u64 v[96:97], v[96:97], 0, s[30:31]
	s_cselect_b32 s30, 0xd800, 0
	v_add_u32_e32 v127, s30, v125
	global_load_dwordx4 v[60:63], v[60:61], off
	ds_read_b128 v[66:69], v127
	ds_read_b128 v[70:73], v127 offset:4608
	ds_read_b128 v[110:113], v127 offset:64
	ds_read_b128 v[128:131], v127 offset:4672
	v_mov_b32_e32 v64, v103
	s_waitcnt vmcnt(7) lgkmcnt(3)
	v_mfma_f32_16x16x32_bf16 v[66:69], v[66:69], v[12:15], 0
	ds_read_b128 v[102:105], v127 offset:9216
	ds_read_b128 v[106:109], v127 offset:13824
	v_mov_b32_e32 v126, v65
	s_waitcnt lgkmcnt(4)
	v_mfma_f32_16x16x32_bf16 v[70:73], v[70:73], v[12:15], 0
	s_bitcmp1_b32 s29, 0
	s_cselect_b32 s30, 0xd800, 0
	s_add_i32 s30, s30, 0
	s_waitcnt vmcnt(6) lgkmcnt(3)
	v_mfma_f32_16x16x32_bf16 v[66:69], v[110:113], v[8:11], v[66:69]
	ds_read_b128 v[110:113], v127 offset:9280
	v_lshl_add_u64 v[98:99], v[98:99], 0, s[86:87]
	v_lshl_add_u64 v[100:101], v[100:101], 0, s[86:87]
	s_waitcnt lgkmcnt(3)
	v_mfma_f32_16x16x32_bf16 v[70:73], v[128:131], v[8:11], v[70:73]
	ds_read_b128 v[128:131], v127 offset:13888
	s_mov_b32 s41, s29
	s_cmp_eq_u32 s28, s29
	s_waitcnt lgkmcnt(3)
	v_mfma_f32_16x16x32_bf16 v[102:105], v[102:105], v[12:15], 0
	s_waitcnt lgkmcnt(2)
	v_mfma_f32_16x16x32_bf16 v[106:109], v[106:109], v[12:15], 0
	s_waitcnt lgkmcnt(1)
	v_mfma_f32_16x16x32_bf16 v[102:105], v[110:113], v[8:11], v[102:105]
	ds_read_b128 v[110:113], v127 offset:128
	s_waitcnt lgkmcnt(1)
	v_mfma_f32_16x16x32_bf16 v[106:109], v[128:131], v[8:11], v[106:109]
	ds_read_b128 v[128:131], v127 offset:4736
	s_waitcnt vmcnt(5) lgkmcnt(1)
	v_mfma_f32_16x16x32_bf16 v[66:69], v[110:113], v[4:7], v[66:69]
	ds_read_b128 v[110:113], v127 offset:9344
	s_waitcnt lgkmcnt(1)
	v_mfma_f32_16x16x32_bf16 v[128:131], v[128:131], v[4:7], v[70:73]
	s_nop 2
	ds_read_b128 v[70:73], v127 offset:13952
	s_waitcnt lgkmcnt(1)
	v_mfma_f32_16x16x32_bf16 v[102:105], v[110:113], v[4:7], v[102:105]
	ds_read_b128 v[110:113], v127 offset:192
	ds_read_b128 v[132:135], v127 offset:4800
	ds_read_b128 v[136:139], v127 offset:9408
	ds_read_b128 v[140:143], v127 offset:14016
	ds_read_b128 v[148:151], v127 offset:18432
	s_waitcnt lgkmcnt(5)
	v_mfma_f32_16x16x32_bf16 v[106:109], v[70:73], v[4:7], v[106:109]
	s_waitcnt vmcnt(4) lgkmcnt(4)
	v_mfma_f32_16x16x32_bf16 v[66:69], v[110:113], v[0:3], v[66:69]
	ds_read_b128 v[152:155], v127 offset:18496
	ds_read_b128 v[112:115], v127 offset:23040
	ds_read_b128 v[72:75], v127 offset:23104
	s_waitcnt lgkmcnt(6)
	v_mfma_f32_16x16x32_bf16 v[128:131], v[132:135], v[0:3], v[128:131]
	s_nop 2
	v_max3_f32 v65, v66, v67, v68
	ds_read_b128 v[132:135], v127 offset:27648
	ds_read_b128 v[174:177], v127 offset:32256
	ds_read_b128 v[178:181], v127 offset:36864
	ds_read_b128 v[182:185], v127 offset:41472
	ds_read_b128 v[186:189], v127 offset:46080
	ds_read_b128 v[190:193], v127 offset:50688
	s_waitcnt lgkmcnt(11)
	v_mfma_f32_16x16x32_bf16 v[136:139], v[136:139], v[0:3], v[102:105]
	v_max_f32_e32 v70, v130, v130
	v_max_f32_e32 v71, v129, v129
	v_max3_f32 v65, v65, v69, v128
	s_waitcnt lgkmcnt(10)
	v_mfma_f32_16x16x32_bf16 v[104:107], v[140:143], v[0:3], v[106:109]
	v_max_f32_e32 v70, v71, v70
	s_nop 1
	v_max_f32_e32 v103, v138, v138
	v_max3_f32 v65, v65, v70, v131
	v_max_f32_e32 v108, v137, v137
	v_max_f32_e32 v71, v108, v103
	s_nop 0
	v_max_f32_e32 v109, v106, v106
	v_max_f32_e32 v110, v105, v105
	v_max3_f32 v65, v65, v136, v71
	v_max_f32_e32 v103, v110, v109
	v_max3_f32 v65, v65, v139, v104
	v_max3_f32 v65, v65, v103, v107
	ds_bpermute_b32 v70, v121, v65
	v_mov_b32_e32 v102, v104
	s_waitcnt lgkmcnt(0)
	v_max_f32_e32 v70, v70, v70
	v_max_f32_e32 v65, v65, v70
	ds_bpermute_b32 v70, v122, v65
	s_waitcnt lgkmcnt(0)
	v_max3_f32 v103, v64, v65, v70
	v_sub_f32_e32 v70, v64, v103
	v_pk_mul_f32 v[64:65], v[102:103], s[56:57]
	v_mul_f32_e32 v70, 0x3e0293ee, v70
	v_fmamk_f32 v66, v66, 0x3e0293ee, v65
	v_fmamk_f32 v67, v67, 0x3e0293ee, v65
	v_fmamk_f32 v68, v68, 0x3e0293ee, v65
	v_fmamk_f32 v69, v69, 0x3e0293ee, v65
	v_fmamk_f32 v71, v128, 0x3e0293ee, v65
	v_fmamk_f32 v108, v129, 0x3e0293ee, v65
	v_fmamk_f32 v109, v130, 0x3e0293ee, v65
	v_fmamk_f32 v110, v131, 0x3e0293ee, v65
	v_fmamk_f32 v111, v136, 0x3e0293ee, v65
	v_fmamk_f32 v130, v137, 0x3e0293ee, v65
	v_fmamk_f32 v131, v138, 0x3e0293ee, v65
	v_fmamk_f32 v136, v139, 0x3e0293ee, v65
	v_add_f32_e32 v64, v64, v65
	v_fmamk_f32 v137, v105, 0x3e0293ee, v65
	v_fmamk_f32 v138, v106, 0x3e0293ee, v65
	v_fmac_f32_e32 v65, 0x3e0293ee, v107
	v_exp_f32_e32 v102, v70
	v_exp_f32_e32 v104, v66
	v_exp_f32_e32 v106, v67
	v_exp_f32_e32 v105, v68
	v_exp_f32_e32 v107, v69
	v_exp_f32_e32 v66, v71
	v_exp_f32_e32 v128, v108
	v_exp_f32_e32 v67, v109
	v_exp_f32_e32 v129, v110
	v_cvt_pk_bf16_f32 v68, v104, v106
	v_cvt_pk_bf16_f32 v69, v105, v107
	v_cvt_pk_bf16_f32 v70, v66, v128
	v_cvt_pk_bf16_f32 v71, v67, v129
	v_mul_f32_e32 v26, v102, v26
	v_mul_f32_e32 v27, v102, v27
	v_mul_f32_e32 v24, v102, v24
	v_mul_f32_e32 v25, v102, v25
	v_mul_f32_e32 v22, v102, v22
	v_mul_f32_e32 v23, v102, v23
	v_mul_f32_e32 v20, v102, v20
	v_mul_f32_e32 v21, v102, v21
	v_mfma_f32_16x16x32_bf16 v[24:27], v[112:115], v[68:71], v[24:27]
	v_add_f32_e64 v114, v66, v128
	v_add_f32_e64 v115, v67, v129
	v_exp_f32_e32 v109, v111
	v_pk_add_f32 v[114:115], v[114:115], v[114:115] op_sel_hi:[0,1]
	v_exp_f32_e32 v111, v130
	v_exp_f32_e32 v147, v131
	v_exp_f32_e32 v173, v136
	v_exp_f32_e32 v108, v64
	v_mul_f32_e32 v18, v102, v18
	v_mul_f32_e32 v19, v102, v19
	v_mul_f32_e32 v16, v102, v16
	v_mul_f32_e32 v17, v102, v17
	v_exp_f32_e32 v110, v137
	v_exp_f32_e32 v112, v65
	v_mfma_f32_16x16x32_bf16 v[20:23], v[132:135], v[68:71], v[20:23]
	v_mul_f32_e64 v58, v58, v102
	v_mul_f32_e64 v59, v59, v102
	v_mul_f32_e32 v56, v102, v56
	v_mul_f32_e32 v57, v102, v57
	v_mul_f32_e32 v54, v102, v54
	v_mul_f32_e32 v55, v102, v55
	v_mul_f32_e32 v52, v102, v52
	v_mul_f32_e32 v53, v102, v53
	v_mul_f32_e32 v66, v102, v50
	v_mul_f32_e32 v67, v102, v51
	v_mul_f32_e32 v64, v102, v48
	v_mul_f32_e32 v65, v102, v49
	v_mul_f32_e32 v130, v102, v46
	v_mul_f32_e32 v131, v102, v47
	v_mul_f32_e32 v128, v102, v44
	v_mul_f32_e32 v129, v102, v45
	v_mul_f32_e32 v134, v102, v30
	v_mul_f32_e32 v135, v102, v31
	v_mul_f32_e32 v132, v102, v28
	v_mul_f32_e32 v133, v102, v29
	v_exp_f32_e32 v114, v138
	v_mfma_f32_16x16x32_bf16 v[16:19], v[148:151], v[68:71], v[16:19]
	v_cvt_pk_bf16_f32 v28, v109, v111
	v_cvt_pk_bf16_f32 v29, v147, v173
	v_cvt_pk_bf16_f32 v30, v108, v110
	v_mfma_f32_16x16x32_bf16 v[56:59], v[174:177], v[68:71], v[56:59]
	v_cvt_pk_bf16_f32 v31, v114, v112
	v_add3_u32 v48, s30, v123, v119
	v_add_f32_e32 v109, v109, v111
	v_mfma_f32_16x16x32_bf16 v[50:53], v[178:181], v[68:71], v[52:55]
	v_add_f32_e32 v111, v147, v173
	v_mfma_f32_16x16x32_bf16 v[44:47], v[182:185], v[68:71], v[64:67]
	v_mfma_f32_16x16x32_bf16 v[64:67], v[186:189], v[68:71], v[128:131]
	v_mfma_f32_16x16x32_bf16 v[68:71], v[190:193], v[68:71], v[132:135]
	s_nop 1
	ds_read_b128 v[128:131], v127 offset:27712
	ds_read_b128 v[132:135], v127 offset:32320
	v_mfma_f32_16x16x32_bf16 v[24:27], v[72:75], v[28:31], v[24:27]
	ds_read_b128 v[72:75], v127 offset:36928
	ds_read_b128 v[136:139], v127 offset:41536
	ds_read_b128 v[140:143], v127 offset:46144
	s_waitcnt lgkmcnt(4)
	v_mfma_f32_16x16x32_bf16 v[20:23], v[128:131], v[28:31], v[20:23]
	ds_read_b128 v[128:131], v127 offset:50752
	v_add3_u32 v127, s30, v117, v118
	s_waitcnt lgkmcnt(3)
	v_mfma_f32_16x16x32_bf16 v[52:55], v[72:75], v[28:31], v[50:53]
	v_add_f32_e64 v72, v104, v106
	v_add_f32_e64 v73, v105, v107
	v_add_u32_e32 v74, 0x9000, v48
	v_add_f32_e32 v75, v72, v73
	v_add_f32_e32 v113, 0, v75
	v_mfma_f32_16x16x32_bf16 v[16:19], v[152:155], v[28:31], v[16:19]
	v_add_f32_e64 v72, v108, v110
	v_add_f32_e64 v73, v109, v111
	v_mfma_f32_16x16x32_bf16 v[56:59], v[132:135], v[28:31], v[56:59]
	v_add_u32_e32 v132, 0x4800, v48
	s_waitcnt vmcnt(3)
	ds_write_b128 v127, v[40:43] offset:9216
	s_waitcnt vmcnt(0)
	ds_write_b128 v127, v[60:63]
	ds_write2_b64 v132, v[32:33], v[34:35] offset1:2
	ds_write2_b64 v74, v[36:37], v[38:39] offset1:2
	s_waitcnt lgkmcnt(0)
	v_mfma_f32_16x16x32_bf16 v[48:51], v[136:139], v[28:31], v[44:47]
	s_barrier
	v_mfma_f32_16x16x32_bf16 v[44:47], v[140:143], v[28:31], v[64:67]
	s_nop 2
	v_add_f32_e64 v64, v114, v112
	v_add_f32_e64 v65, v115, v113
	v_mfma_f32_16x16x32_bf16 v[28:31], v[128:131], v[28:31], v[68:71]
	v_add_f32_e64 v64, v72, v64
	v_add_f32_e64 v65, v73, v65
	v_add_f32_e32 v65, v64, v65
	v_fmac_f32_e32 v65, v126, v102
	s_cbranch_scc0 .LBB0_29
	v_add3_u32 v100, s30, v120, v124
	ds_read_b128 v[32:35], v100
	ds_read_b128 v[36:39], v100 offset:64
	ds_read_b128 v[40:43], v100 offset:4608
	ds_read_b128 v[60:63], v100 offset:4672
	ds_read_b128 v[66:69], v100 offset:128
	s_lshl_b32 s84, s40, 1
	s_waitcnt lgkmcnt(4)
	v_mfma_f32_16x16x32_bf16 v[32:35], v[32:35], v[12:15], 0
	s_waitcnt lgkmcnt(3)
	v_mfma_f32_16x16x32_bf16 v[32:35], v[36:39], v[8:11], v[32:35]
	ds_read_b128 v[36:39], v100 offset:192
	s_waitcnt lgkmcnt(1)
	v_mfma_f32_16x16x32_bf16 v[32:35], v[66:69], v[4:7], v[32:35]
	ds_read_b128 v[66:69], v100 offset:9344
	v_mfma_f32_16x16x32_bf16 v[40:43], v[40:43], v[12:15], 0
	s_waitcnt lgkmcnt(1)
	v_mfma_f32_16x16x32_bf16 v[32:35], v[36:39], v[0:3], v[32:35]
	ds_read_b128 v[36:39], v100 offset:4736
	v_mfma_f32_16x16x32_bf16 v[40:43], v[60:63], v[8:11], v[40:43]
	ds_read_b128 v[60:63], v100 offset:4800
	s_nop 4
	v_max3_f32 v64, v32, v33, v34
	s_waitcnt lgkmcnt(1)
	v_mfma_f32_16x16x32_bf16 v[36:39], v[36:39], v[4:7], v[40:43]
	s_nop 2
	ds_read_b128 v[40:43], v100 offset:9216
	s_waitcnt lgkmcnt(1)
	v_mfma_f32_16x16x32_bf16 v[36:39], v[60:63], v[0:3], v[36:39]
	ds_read_b128 v[60:63], v100 offset:9280
	s_waitcnt lgkmcnt(1)
	v_mfma_f32_16x16x32_bf16 v[40:43], v[40:43], v[12:15], 0
	s_nop 4
	v_max3_f32 v64, v64, v35, v36
	s_waitcnt lgkmcnt(0)
	v_mfma_f32_16x16x32_bf16 v[40:43], v[60:63], v[8:11], v[40:43]
	ds_read_b128 v[60:63], v100 offset:9408
	v_mfma_f32_16x16x32_bf16 v[40:43], v[66:69], v[4:7], v[40:43]
	ds_read_b128 v[66:69], v100 offset:13824
	ds_read_b128 v[70:73], v100 offset:13888
	s_waitcnt lgkmcnt(1)
	v_mfma_f32_16x16x32_bf16 v[12:15], v[66:69], v[12:15], 0
	v_max_f32_e32 v66, v38, v38
	v_max_f32_e32 v67, v37, v37
	v_mfma_f32_16x16x32_bf16 v[40:43], v[60:63], v[0:3], v[40:43]
	ds_read_b128 v[60:63], v100 offset:13952
	ds_read_b128 v[96:99], v100 offset:14016
	s_waitcnt lgkmcnt(2)
	v_mfma_f32_16x16x32_bf16 v[8:11], v[70:73], v[8:11], v[12:15]
	s_waitcnt lgkmcnt(1)
	v_mfma_f32_16x16x32_bf16 v[4:7], v[60:63], v[4:7], v[8:11]
	s_nop 0
	v_max_f32_e32 v12, v67, v66
	v_max_f32_e32 v13, v42, v42
	v_max3_f32 v12, v64, v12, v39
	s_waitcnt lgkmcnt(0)
	v_mfma_f32_16x16x32_bf16 v[0:3], v[96:99], v[0:3], v[4:7]
	v_max_f32_e32 v8, v41, v41
	v_max_f32_e32 v8, v8, v13
	v_max3_f32 v8, v12, v40, v8
	s_nop 4
	v_max_f32_e32 v5, v2, v2
	v_max_f32_e32 v6, v1, v1
	v_max3_f32 v4, v8, v43, v0
	v_max_f32_e32 v5, v6, v5
	v_max3_f32 v4, v4, v5, v3
	ds_bpermute_b32 v5, v121, v4
	s_waitcnt lgkmcnt(0)
	v_max_f32_e32 v5, v5, v5
	v_max_f32_e32 v60, v4, v5
	ds_bpermute_b32 v61, v122, v60
	ds_read_b128 v[4:7], v100 offset:18432
	ds_read_b128 v[8:11], v100 offset:18496
	ds_read_b128 v[12:15], v100 offset:23040
	s_waitcnt lgkmcnt(3)
	v_max3_f32 v61, v103, v60, v61
	v_sub_f32_e32 v60, v103, v61
	v_mul_f32_e32 v60, 0x3e0293ee, v60
	v_exp_f32_e32 v64, v60
	v_mov_b32_e32 v60, v3
	v_pk_mul_f32 v[60:61], v[60:61], s[56:57]
	v_pk_mul_f32 v[22:23], v[22:23], v[64:65] op_sel_hi:[1,0]
	v_fmamk_f32 v3, v32, 0x3e0293ee, v61
	v_exp_f32_e32 v66, v3
	v_fmamk_f32 v3, v33, 0x3e0293ee, v61
	v_fmamk_f32 v33, v37, 0x3e0293ee, v61
	v_exp_f32_e32 v68, v3
	v_fmamk_f32 v3, v34, 0x3e0293ee, v61
	v_fmamk_f32 v32, v36, 0x3e0293ee, v61
	v_exp_f32_e32 v36, v33
	v_fmamk_f32 v33, v38, 0x3e0293ee, v61
	v_fmamk_f32 v34, v39, 0x3e0293ee, v61
	v_exp_f32_e32 v32, v32
	v_exp_f32_e32 v33, v33
	v_exp_f32_e32 v37, v34
	v_exp_f32_e32 v67, v3
	v_fmamk_f32 v3, v35, 0x3e0293ee, v61
	v_exp_f32_e32 v69, v3
	v_fmamk_f32 v3, v40, 0x3e0293ee, v61
	v_fmamk_f32 v0, v0, 0x3e0293ee, v61
	v_pk_add_f32 v[34:35], v[32:33], v[36:37]
	v_exp_f32_e32 v73, v3
	v_fmamk_f32 v3, v41, 0x3e0293ee, v61
	v_exp_f32_e32 v72, v0
	v_fmamk_f32 v0, v1, 0x3e0293ee, v61
	v_pk_add_f32 v[70:71], v[34:35], v[34:35] op_sel_hi:[0,1]
	v_exp_f32_e32 v75, v3
	v_fmamk_f32 v3, v42, 0x3e0293ee, v61
	v_exp_f32_e32 v74, v0
	v_fmamk_f32 v0, v2, 0x3e0293ee, v61
	v_exp_f32_e32 v97, v3
	v_fmamk_f32 v3, v43, 0x3e0293ee, v61
	v_exp_f32_e32 v70, v0
	v_add_f32_e32 v0, v60, v61
	v_exp_f32_e32 v98, v3
	v_exp_f32_e32 v96, v0
	v_pk_mul_f32 v[2:3], v[18:19], v[64:65] op_sel_hi:[1,0]
	v_pk_mul_f32 v[0:1], v[16:17], v[64:65] op_sel_hi:[1,0]
	v_cvt_pk_bf16_f32 v16, v66, v68
	v_cvt_pk_bf16_f32 v17, v67, v69
	v_cvt_pk_bf16_f32 v18, v32, v36
	v_cvt_pk_bf16_f32 v19, v33, v37
	v_cvt_pk_bf16_f32 v32, v73, v75
	v_cvt_pk_bf16_f32 v33, v97, v98
	s_waitcnt lgkmcnt(2)
	v_mfma_f32_16x16x32_bf16 v[0:3], v[4:7], v[16:19], v[0:3]
	ds_read_b128 v[4:7], v100 offset:23104
	v_cvt_pk_bf16_f32 v34, v72, v74
	v_cvt_pk_bf16_f32 v35, v70, v96
	v_pk_mul_f32 v[20:21], v[20:21], v[64:65] op_sel_hi:[1,0]
	v_pk_mul_f32 v[54:55], v[54:55], v[64:65] op_sel_hi:[1,0]
	s_waitcnt lgkmcnt(2)
	v_mfma_f32_16x16x32_bf16 v[0:3], v[8:11], v[32:35], v[0:3]
	v_mul_f32_e64 v10, v26, v64
	v_mul_f32_e64 v11, v27, v64
	v_pk_mul_f32 v[8:9], v[24:25], v[64:65] op_sel_hi:[1,0]
	v_pk_mul_f32 v[26:27], v[58:59], v[64:65] op_sel_hi:[1,0]
	v_pk_mul_f32 v[24:25], v[56:57], v[64:65] op_sel_hi:[1,0]
	s_waitcnt lgkmcnt(1)
	v_mfma_f32_16x16x32_bf16 v[8:11], v[12:15], v[16:19], v[8:11]
	ds_read_b128 v[12:15], v100 offset:27648
	v_pk_mul_f32 v[52:53], v[52:53], v[64:65] op_sel_hi:[1,0]
	v_pk_add_f32 v[66:67], v[66:67], v[68:69]
	s_waitcnt lgkmcnt(1)
	v_mfma_f32_16x16x32_bf16 v[4:7], v[4:7], v[32:35], v[8:11]
	v_add_f32_e32 v66, v66, v67
	v_add_f32_e32 v73, v73, v75
	v_add_f32_e32 v75, v97, v98
	ds_read_b128 v[8:11], v100 offset:27712
	s_waitcnt lgkmcnt(1)
	v_mfma_f32_16x16x32_bf16 v[12:15], v[12:15], v[16:19], v[20:23]
	v_add_f32_e32 v97, 0, v66
	v_pk_mul_f32 v[30:31], v[30:31], v[64:65] op_sel_hi:[1,0]
	s_nop 0
	ds_read_b128 v[20:23], v100 offset:32256
	s_waitcnt lgkmcnt(1)
	v_mfma_f32_16x16x32_bf16 v[8:11], v[8:11], v[32:35], v[12:15]
	s_nop 2
	ds_read_b128 v[12:15], v100 offset:32320
	v_pk_mul_f32 v[28:29], v[28:29], v[64:65] op_sel_hi:[1,0]
	s_waitcnt lgkmcnt(1)
	v_mfma_f32_16x16x32_bf16 v[20:23], v[20:23], v[16:19], v[24:27]
	s_nop 2
	ds_read_b128 v[24:27], v100 offset:36864
	ds_read_b128 v[36:39], v100 offset:36928
	s_waitcnt lgkmcnt(1)
	v_mfma_f32_16x16x32_bf16 v[24:27], v[24:27], v[16:19], v[52:55]
	v_mfma_f32_16x16x32_bf16 v[12:15], v[12:15], v[32:35], v[20:23]
	s_nop 2
	ds_read_b128 v[20:23], v100 offset:41472
	ds_read_b128 v[40:43], v100 offset:41536
	ds_read_b128 v[52:55], v100 offset:46080
	ds_read_b128 v[56:59], v100 offset:46144
	ds_read_b128 v[60:63], v100 offset:50688
	s_waitcnt lgkmcnt(5)
	v_mfma_f32_16x16x32_bf16 v[24:27], v[36:39], v[32:35], v[24:27]
	v_mul_f32_e64 v38, v50, v64
	v_mul_f32_e64 v39, v51, v64
	v_pk_mul_f32 v[36:37], v[48:49], v[64:65] op_sel_hi:[1,0]
	s_waitcnt lgkmcnt(4)
	s_nop 0
	v_mfma_f32_16x16x32_bf16 v[20:23], v[20:23], v[16:19], v[36:39]
	s_waitcnt lgkmcnt(3)
	v_mfma_f32_16x16x32_bf16 v[20:23], v[40:43], v[32:35], v[20:23]
	v_add_f32_e64 v40, v72, v74
	v_add_f32_e64 v41, v73, v75
	v_pk_add_f32 v[42:43], v[70:71], v[96:97]
	v_pk_mul_f32 v[36:37], v[44:45], v[64:65] op_sel_hi:[1,0]
	v_pk_add_f32 v[40:41], v[40:41], v[42:43]
	v_pk_mul_f32 v[38:39], v[46:47], v[64:65] op_sel_hi:[1,0]
	v_add_f32_e32 v44, v40, v41
	v_fmac_f32_e32 v44, v65, v64
	ds_bpermute_b32 v45, v121, v44
	s_waitcnt lgkmcnt(3)
	v_mfma_f32_16x16x32_bf16 v[36:39], v[52:55], v[16:19], v[36:39]
	ds_read_b128 v[40:43], v100 offset:50752
	s_waitcnt lgkmcnt(0)
	s_barrier
	v_mfma_f32_16x16x32_bf16 v[16:19], v[60:63], v[16:19], v[28:31]
	s_nop 2
	v_add_f32_e32 v28, v44, v45
	ds_bpermute_b32 v29, v122, v28
	v_mfma_f32_16x16x32_bf16 v[36:39], v[56:59], v[32:35], v[36:39]
	s_waitcnt lgkmcnt(0)
	v_add_f32_e32 v28, v28, v29
	v_div_scale_f32 v29, s[28:29], v28, v28, 1.0
	v_rcp_f32_e32 v30, v29
	v_mfma_f32_16x16x32_bf16 v[16:19], v[40:43], v[32:35], v[16:19]
	v_fma_f32 v31, -v29, v30, 1.0
	v_fmac_f32_e32 v30, v31, v30
	v_div_scale_f32 v31, vcc, 1.0, v28, 1.0
	v_mul_f32_e32 v32, v31, v30
	v_fma_f32 v33, -v29, v32, v31
	v_fmac_f32_e32 v32, v33, v30
	v_fma_f32 v29, -v29, v32, v31
	v_div_fmas_f32 v29, v29, v30, v32
	v_div_fixup_f32 v28, v29, v28, 1.0
	v_lshl_add_u64 v[30:31], s[24:25], 0, v[94:95]
	v_lshl_add_u64 v[30:31], v[30:31], 0, s[84:85]
	v_pk_mul_f32 v[2:3], v[2:3], v[28:29] op_sel_hi:[1,0]
	v_pk_mul_f32 v[0:1], v[0:1], v[28:29] op_sel_hi:[1,0]
	v_lshl_add_u64 v[30:31], v[30:31], 0, v[144:145]
	v_cvt_pk_bf16_f32 v0, v0, v1
	v_cvt_pk_bf16_f32 v1, v2, v3
	global_store_dwordx2 v[30:31], v[0:1], off
	v_pk_mul_f32 v[0:1], v[6:7], v[28:29] op_sel_hi:[1,0]
	v_pk_mul_f32 v[2:3], v[4:5], v[28:29] op_sel_hi:[1,0]
	s_nop 0
	v_cvt_pk_bf16_f32 v2, v2, v3
	v_cvt_pk_bf16_f32 v3, v0, v1
	global_store_dwordx2 v[30:31], v[2:3], off offset:32
	v_pk_mul_f32 v[0:1], v[10:11], v[28:29] op_sel_hi:[1,0]
	v_pk_mul_f32 v[2:3], v[8:9], v[28:29] op_sel_hi:[1,0]
	s_nop 0
	v_cvt_pk_bf16_f32 v2, v2, v3
	v_cvt_pk_bf16_f32 v3, v0, v1
	global_store_dwordx2 v[30:31], v[2:3], off offset:64
	v_pk_mul_f32 v[0:1], v[14:15], v[28:29] op_sel_hi:[1,0]
	v_pk_mul_f32 v[2:3], v[12:13], v[28:29] op_sel_hi:[1,0]
	s_nop 0
	v_cvt_pk_bf16_f32 v2, v2, v3
	v_cvt_pk_bf16_f32 v3, v0, v1
	global_store_dwordx2 v[30:31], v[2:3], off offset:96
	v_pk_mul_f32 v[0:1], v[26:27], v[28:29] op_sel_hi:[1,0]
	v_pk_mul_f32 v[2:3], v[24:25], v[28:29] op_sel_hi:[1,0]
	s_nop 0
	v_cvt_pk_bf16_f32 v2, v2, v3
	v_cvt_pk_bf16_f32 v3, v0, v1
	global_store_dwordx2 v[30:31], v[2:3], off offset:128
	v_pk_mul_f32 v[0:1], v[22:23], v[28:29] op_sel_hi:[1,0]
	v_pk_mul_f32 v[2:3], v[20:21], v[28:29] op_sel_hi:[1,0]
	s_nop 0
	v_cvt_pk_bf16_f32 v2, v2, v3
	v_cvt_pk_bf16_f32 v3, v0, v1
	global_store_dwordx2 v[30:31], v[2:3], off offset:160
	v_pk_mul_f32 v[0:1], v[38:39], v[28:29] op_sel_hi:[1,0]
	v_pk_mul_f32 v[2:3], v[36:37], v[28:29] op_sel_hi:[1,0]
	s_nop 0
	v_cvt_pk_bf16_f32 v2, v2, v3
	v_cvt_pk_bf16_f32 v3, v0, v1
	global_store_dwordx2 v[30:31], v[2:3], off offset:192
	s_load_dword s28, s[80:81], 0x0
	v_pk_mul_f32 v[0:1], v[18:19], v[28:29] op_sel_hi:[1,0]
	v_pk_mul_f32 v[2:3], v[16:17], v[28:29] op_sel_hi:[1,0]
	s_waitcnt lgkmcnt(0)
	s_add_i32 s33, s33, s28
	v_cvt_pk_bf16_f32 v2, v2, v3
	v_cvt_pk_bf16_f32 v3, v0, v1
	s_cmpk_gt_i32 s33, 0x1ff
	global_store_dwordx2 v[30:31], v[2:3], off offset:224
	s_cbranch_scc0 .LBB0_24
